# deferred epilogue pieces interleaved with MFMAs use two plain multiplies instead of one packed multiply
# baseline (speedup 1.0000x reference)
.Lmy_b16_pdefer:
	s_add_u32 s1, s12, 0xfffc0080
	s_addc_u32 s14, s13, -1
	s_add_i32 s33, 0, 0x10000
	s_cmp_eq_u32 s73, 12
	s_cselect_b32 s29, s11, s14
	s_cselect_b32 s28, s30, s1
	v_add_u32_e32 v100, s33, v154
	s_cselect_b32 s15, s31, s55
	s_cselect_b32 s14, s47, s54
	s_add_i32 s1, 0, 0x14000
	ds_read_b128 v[144:147], v100
	ds_read_b128 v[148:151], v100 offset:1024
	ds_read_b128 v[158:161], v100 offset:2048
	ds_read_b128 v[162:165], v100 offset:3072
	v_add_u32_e32 v100, s1, v154
	ds_read_b128 v[166:169], v100
	ds_read_b128 v[170:173], v100 offset:1024
	ds_read_b128 v[174:177], v100 offset:2048
	ds_read_b128 v[178:181], v100 offset:3072
	v_lshl_add_u64 v[152:153], s[12:13], 0, v[140:141]
	s_add_i32 m0, s41, 0xc000
	ds_read_b128 v[182:185], v156
	ds_read_b128 v[186:189], v156 offset:1024
	ds_read_b128 v[190:193], v156 offset:2048
	ds_read_b128 v[194:197], v156 offset:3072
	ds_read_b128 v[198:201], v156 offset:4096
	ds_read_b128 v[202:205], v156 offset:5120
	ds_read_b128 v[208:211], v156 offset:6144
	ds_read_b128 v[226:229], v156 offset:7168
	global_load_lds_dwordx4 v[152:153], off
	v_lshl_add_u64 v[152:153], s[12:13], 0, v[142:143]
	s_add_i32 m0, s41, 0xe000
	s_nop 0
	global_load_lds_dwordx4 v[152:153], off
	v_and_b32_e32 v100, 3, v224
	v_lshlrev_b32_e32 v100, 6, v100
	v_and_or_b32 v100, v224, 60, v100
	v_mov_b32_e32 v152, v247
	v_fmamk_f32 v234, v236, 0x3a800000, v207
	v_rsq_f32_e32 v234, v234
	s_nop 0
	v_mul_f32_e32 v234, s36, v234
	v_pk_mul_f32 v[126:127], v[126:127], v[234:235] op_sel_hi:[1,0]
	v_pk_mul_f32 v[128:129], v[128:129], v[234:235] op_sel_hi:[1,0]
	v_pk_mul_f32 v[122:123], v[122:123], v[234:235] op_sel_hi:[1,0]
	v_pk_mul_f32 v[124:125], v[124:125], v[234:235] op_sel_hi:[1,0]
	v_cvt_pk_bf16_f32 v126, v126, v127
	v_cvt_pk_bf16_f32 v127, v128, v129
	v_cvt_pk_bf16_f32 v128, v122, v123
	v_cvt_pk_bf16_f32 v129, v124, v125
	ds_bpermute_b32 v122, v100, v126
	ds_bpermute_b32 v123, v100, v127
	ds_bpermute_b32 v124, v100, v128
	ds_bpermute_b32 v125, v100, v129
	v_fmamk_f32 v234, v237, 0x3a800000, v207
	v_rsq_f32_e32 v234, v234
	s_nop 0
	v_mul_f32_e32 v234, s36, v234
	v_pk_mul_f32 v[110:111], v[110:111], v[234:235] op_sel_hi:[1,0]
	v_pk_mul_f32 v[112:113], v[112:113], v[234:235] op_sel_hi:[1,0]
	v_pk_mul_f32 v[106:107], v[106:107], v[234:235] op_sel_hi:[1,0]
	v_pk_mul_f32 v[108:109], v[108:109], v[234:235] op_sel_hi:[1,0]
	v_cvt_pk_bf16_f32 v110, v110, v111
	v_cvt_pk_bf16_f32 v111, v112, v113
	v_cvt_pk_bf16_f32 v112, v106, v107
	v_cvt_pk_bf16_f32 v113, v108, v109
	ds_bpermute_b32 v106, v100, v110
	ds_bpermute_b32 v107, v100, v111
	ds_bpermute_b32 v108, v100, v112
	ds_bpermute_b32 v109, v100, v113
	s_waitcnt lgkmcnt(4)
	global_store_dwordx4 v152, v[122:125], s[2:3] nt
	v_add_u32_e32 v152, s0, v152
	v_fmamk_f32 v234, v238, 0x3a800000, v207
	v_rsq_f32_e32 v234, v234
	s_nop 0
	v_mul_f32_e32 v234, s36, v234
	v_pk_mul_f32 v[92:93], v[92:93], v[234:235] op_sel_hi:[1,0]
	v_pk_mul_f32 v[94:95], v[94:95], v[234:235] op_sel_hi:[1,0]
	v_pk_mul_f32 v[88:89], v[88:89], v[234:235] op_sel_hi:[1,0]
	v_pk_mul_f32 v[90:91], v[90:91], v[234:235] op_sel_hi:[1,0]
	v_cvt_pk_bf16_f32 v92, v92, v93
	v_cvt_pk_bf16_f32 v93, v94, v95
	v_cvt_pk_bf16_f32 v94, v88, v89
	v_cvt_pk_bf16_f32 v95, v90, v91
	ds_bpermute_b32 v88, v100, v92
	ds_bpermute_b32 v89, v100, v93
	ds_bpermute_b32 v90, v100, v94
	ds_bpermute_b32 v91, v100, v95
	s_waitcnt lgkmcnt(4)
	global_store_dwordx4 v152, v[106:109], s[2:3] nt
	v_add_u32_e32 v152, s0, v152
	v_fmamk_f32 v234, v239, 0x3a800000, v207
	v_rsq_f32_e32 v234, v234
	s_nop 0
	v_mul_f32_e32 v234, s36, v234
	v_pk_mul_f32 v[76:77], v[76:77], v[234:235] op_sel_hi:[1,0]
	v_pk_mul_f32 v[78:79], v[78:79], v[234:235] op_sel_hi:[1,0]
	v_pk_mul_f32 v[72:73], v[72:73], v[234:235] op_sel_hi:[1,0]
	v_pk_mul_f32 v[74:75], v[74:75], v[234:235] op_sel_hi:[1,0]
	v_cvt_pk_bf16_f32 v76, v76, v77
	v_cvt_pk_bf16_f32 v77, v78, v79
	v_cvt_pk_bf16_f32 v78, v72, v73
	v_cvt_pk_bf16_f32 v79, v74, v75
	ds_bpermute_b32 v72, v100, v76
	ds_bpermute_b32 v73, v100, v77
	ds_bpermute_b32 v74, v100, v78
	ds_bpermute_b32 v75, v100, v79
	s_waitcnt lgkmcnt(4)
	global_store_dwordx4 v152, v[88:91], s[2:3] nt
	v_add_u32_e32 v152, s0, v152
	s_waitcnt lgkmcnt(0)
	global_store_dwordx4 v152, v[72:75], s[2:3] nt
	s_waitcnt vmcnt(12)
	s_waitcnt lgkmcnt(0)
	s_barrier
	s_setprio 1
	s_waitcnt lgkmcnt(0)
	v_mfma_f32_16x16x32_bf16 v[126:129], v[144:147], v[182:185], 0
	v_add_u32_e32 v153, s32, v247
	v_fmamk_f32 v230, v236, 0x3a800000, v207
	v_rsq_f32_e32 v230, v230
	s_nop 0
	v_mul_f32_e32 v230, s36, v230
	v_mfma_f32_16x16x32_bf16 v[122:125], v[158:161], v[182:185], 0
	v_mul_f32_e32 v118, v230, v118
	v_mul_f32_e32 v119, v230, v119
	v_mul_f32_e32 v120, v230, v120
	v_mul_f32_e32 v121, v230, v121
	v_mul_f32_e32 v114, v230, v114
	v_mul_f32_e32 v115, v230, v115
	v_mfma_f32_16x16x32_bf16 v[110:113], v[144:147], v[190:193], 0
	v_mul_f32_e32 v116, v230, v116
	v_mul_f32_e32 v117, v230, v117
	v_cvt_pk_bf16_f32 v118, v118, v119
	v_cvt_pk_bf16_f32 v119, v120, v121
	v_cvt_pk_bf16_f32 v120, v114, v115
	v_cvt_pk_bf16_f32 v121, v116, v117
	v_mfma_f32_16x16x32_bf16 v[106:109], v[158:161], v[190:193], 0
	ds_bpermute_b32 v114, v100, v118
	ds_bpermute_b32 v115, v100, v119
	ds_bpermute_b32 v116, v100, v120
	ds_bpermute_b32 v117, v100, v121
	v_fmamk_f32 v230, v237, 0x3a800000, v207
	v_rsq_f32_e32 v230, v230
	v_mfma_f32_16x16x32_bf16 v[92:95], v[144:147], v[198:201], 0
	s_nop 0
	v_mul_f32_e32 v230, s36, v230
	v_mul_f32_e32 v102, v230, v102
	v_mul_f32_e32 v103, v230, v103
	v_mul_f32_e32 v104, v230, v104
	v_mfma_f32_16x16x32_bf16 v[88:91], v[158:161], v[198:201], 0
	v_mul_f32_e32 v105, v230, v105
	v_mul_f32_e32 v96, v230, v96
	v_mul_f32_e32 v97, v230, v97
	v_mul_f32_e32 v98, v230, v98
	v_mul_f32_e32 v99, v230, v99
	v_cvt_pk_bf16_f32 v102, v102, v103
	v_mfma_f32_16x16x32_bf16 v[76:79], v[144:147], v[208:211], 0
	v_cvt_pk_bf16_f32 v103, v104, v105
	v_cvt_pk_bf16_f32 v104, v96, v97
	v_cvt_pk_bf16_f32 v105, v98, v99
	ds_bpermute_b32 v96, v100, v102
	ds_bpermute_b32 v97, v100, v103
	ds_bpermute_b32 v98, v100, v104
	v_mfma_f32_16x16x32_bf16 v[72:75], v[158:161], v[208:211], 0
	ds_bpermute_b32 v99, v100, v105
	s_waitcnt lgkmcnt(4)
	global_store_dwordx4 v153, v[114:117], s[2:3] nt
	v_add_u32_e32 v153, s0, v153
	v_fmamk_f32 v230, v238, 0x3a800000, v207
	v_rsq_f32_e32 v230, v230
	v_mfma_f32_16x16x32_bf16 v[126:129], v[148:151], v[186:189], v[126:129]
	s_nop 0
	v_mul_f32_e32 v230, s36, v230
	v_mul_f32_e32 v84, v230, v84
	v_mul_f32_e32 v85, v230, v85
	v_mul_f32_e32 v86, v230, v86
	v_mfma_f32_16x16x32_bf16 v[122:125], v[162:165], v[186:189], v[122:125]
	v_mul_f32_e32 v87, v230, v87
	v_mul_f32_e32 v80, v230, v80
	v_mul_f32_e32 v81, v230, v81
	v_mul_f32_e32 v82, v230, v82
	v_mul_f32_e32 v83, v230, v83
	v_cvt_pk_bf16_f32 v84, v84, v85
	v_mfma_f32_16x16x32_bf16 v[110:113], v[148:151], v[194:197], v[110:113]
	v_cvt_pk_bf16_f32 v85, v86, v87
	v_cvt_pk_bf16_f32 v86, v80, v81
	v_cvt_pk_bf16_f32 v87, v82, v83
	ds_bpermute_b32 v80, v100, v84
	ds_bpermute_b32 v81, v100, v85
	ds_bpermute_b32 v82, v100, v86
	v_mfma_f32_16x16x32_bf16 v[106:109], v[162:165], v[194:197], v[106:109]
	ds_bpermute_b32 v83, v100, v87
	s_waitcnt lgkmcnt(4)
	global_store_dwordx4 v153, v[96:99], s[2:3] nt
	v_add_u32_e32 v153, s0, v153
	v_fmamk_f32 v230, v239, 0x3a800000, v207
	v_rsq_f32_e32 v230, v230
	v_mfma_f32_16x16x32_bf16 v[92:95], v[148:151], v[202:205], v[92:95]
	s_nop 0
	v_mul_f32_e32 v230, s36, v230
	v_mul_f32_e32 v68, v230, v68
	v_mul_f32_e32 v69, v230, v69
	v_mul_f32_e32 v70, v230, v70
	v_mfma_f32_16x16x32_bf16 v[88:91], v[162:165], v[202:205], v[88:91]
	v_mul_f32_e32 v71, v230, v71
	v_mul_f32_e32 v64, v230, v64
	v_mul_f32_e32 v65, v230, v65
	v_mul_f32_e32 v66, v230, v66
	v_mul_f32_e32 v67, v230, v67
	v_cvt_pk_bf16_f32 v68, v68, v69
	v_mfma_f32_16x16x32_bf16 v[76:79], v[148:151], v[226:229], v[76:79]
	v_cvt_pk_bf16_f32 v69, v70, v71
	v_cvt_pk_bf16_f32 v70, v64, v65
	v_cvt_pk_bf16_f32 v71, v66, v67
	ds_bpermute_b32 v64, v100, v68
	ds_bpermute_b32 v65, v100, v69
	ds_bpermute_b32 v66, v100, v70
	v_mfma_f32_16x16x32_bf16 v[72:75], v[162:165], v[226:229], v[72:75]
	ds_bpermute_b32 v67, v100, v71
	s_waitcnt lgkmcnt(4)
	global_store_dwordx4 v153, v[80:83], s[2:3] nt
	v_add_u32_e32 v153, s0, v153
	s_waitcnt lgkmcnt(0)
	global_store_dwordx4 v153, v[64:67], s[2:3] nt
	s_setprio 0
	s_setprio 1
	v_mfma_f32_16x16x32_bf16 v[118:121], v[166:169], v[182:185], 0
	v_mov_b32_e32 v152, v247
	v_fmamk_f32 v234, v240, 0x3a800000, v207
	v_rsq_f32_e32 v234, v234
	s_nop 0
	v_mul_f32_e32 v234, s36, v234
	v_mfma_f32_16x16x32_bf16 v[114:117], v[174:177], v[182:185], 0
	v_mul_f32_e32 v60, v234, v60
	v_mul_f32_e32 v61, v234, v61
	v_mul_f32_e32 v62, v234, v62
	v_mul_f32_e32 v63, v234, v63
	v_mul_f32_e32 v56, v234, v56
	v_mul_f32_e32 v57, v234, v57
	v_mfma_f32_16x16x32_bf16 v[102:105], v[166:169], v[190:193], 0
	v_mul_f32_e32 v58, v234, v58
	v_mul_f32_e32 v59, v234, v59
	v_cvt_pk_bf16_f32 v60, v60, v61
	v_cvt_pk_bf16_f32 v61, v62, v63
	v_cvt_pk_bf16_f32 v62, v56, v57
	v_cvt_pk_bf16_f32 v63, v58, v59
	v_mfma_f32_16x16x32_bf16 v[96:99], v[174:177], v[190:193], 0
	ds_bpermute_b32 v56, v100, v60
	ds_bpermute_b32 v57, v100, v61
	ds_bpermute_b32 v58, v100, v62
	ds_bpermute_b32 v59, v100, v63
	v_fmamk_f32 v234, v244, 0x3a800000, v207
	v_rsq_f32_e32 v234, v234
	v_mfma_f32_16x16x32_bf16 v[84:87], v[166:169], v[198:201], 0
	s_nop 0
	v_mul_f32_e32 v234, s36, v234
	v_mul_f32_e32 v44, v234, v44
	v_mul_f32_e32 v45, v234, v45
	v_mul_f32_e32 v46, v234, v46
	v_mfma_f32_16x16x32_bf16 v[80:83], v[174:177], v[198:201], 0
	v_mul_f32_e32 v47, v234, v47
	v_mul_f32_e32 v40, v234, v40
	v_mul_f32_e32 v41, v234, v41
	v_mul_f32_e32 v42, v234, v42
	v_mul_f32_e32 v43, v234, v43
	v_cvt_pk_bf16_f32 v44, v44, v45
	v_mfma_f32_16x16x32_bf16 v[68:71], v[166:169], v[208:211], 0
	v_cvt_pk_bf16_f32 v45, v46, v47
	v_cvt_pk_bf16_f32 v46, v40, v41
	v_cvt_pk_bf16_f32 v47, v42, v43
	ds_bpermute_b32 v40, v100, v44
	ds_bpermute_b32 v41, v100, v45
	ds_bpermute_b32 v42, v100, v46
	v_mfma_f32_16x16x32_bf16 v[64:67], v[174:177], v[208:211], 0
	ds_bpermute_b32 v43, v100, v47
	s_waitcnt lgkmcnt(4)
	global_store_dwordx4 v152, v[56:59], s[90:91] nt
	v_add_u32_e32 v152, s0, v152
	v_fmamk_f32 v234, v245, 0x3a800000, v207
	v_rsq_f32_e32 v234, v234
	v_mfma_f32_16x16x32_bf16 v[118:121], v[170:173], v[186:189], v[118:121]
	s_nop 0
	v_mul_f32_e32 v234, s36, v234
	v_mul_f32_e32 v28, v234, v28
	v_mul_f32_e32 v29, v234, v29
	v_mul_f32_e32 v30, v234, v30
	v_mfma_f32_16x16x32_bf16 v[114:117], v[178:181], v[186:189], v[114:117]
	v_mul_f32_e32 v31, v234, v31
	v_mul_f32_e32 v24, v234, v24
	v_mul_f32_e32 v25, v234, v25
	v_mul_f32_e32 v26, v234, v26
	v_mul_f32_e32 v27, v234, v27
	v_cvt_pk_bf16_f32 v28, v28, v29
	v_mfma_f32_16x16x32_bf16 v[102:105], v[170:173], v[194:197], v[102:105]
	v_cvt_pk_bf16_f32 v29, v30, v31
	v_cvt_pk_bf16_f32 v30, v24, v25
	v_cvt_pk_bf16_f32 v31, v26, v27
	ds_bpermute_b32 v24, v100, v28
	ds_bpermute_b32 v25, v100, v29
	ds_bpermute_b32 v26, v100, v30
	v_mfma_f32_16x16x32_bf16 v[96:99], v[178:181], v[194:197], v[96:99]
	ds_bpermute_b32 v27, v100, v31
	s_waitcnt lgkmcnt(4)
	global_store_dwordx4 v152, v[40:43], s[90:91] nt
	v_add_u32_e32 v152, s0, v152
	v_fmamk_f32 v234, v246, 0x3a800000, v207
	v_rsq_f32_e32 v234, v234
	v_mfma_f32_16x16x32_bf16 v[84:87], v[170:173], v[202:205], v[84:87]
	s_nop 0
	v_mul_f32_e32 v234, s36, v234
	v_mul_f32_e32 v12, v234, v12
	v_mul_f32_e32 v13, v234, v13
	v_mul_f32_e32 v14, v234, v14
	v_mfma_f32_16x16x32_bf16 v[80:83], v[178:181], v[202:205], v[80:83]
	v_mul_f32_e32 v15, v234, v15
	v_mul_f32_e32 v8, v234, v8
	v_mul_f32_e32 v9, v234, v9
	v_mul_f32_e32 v10, v234, v10
	v_mul_f32_e32 v11, v234, v11
	v_cvt_pk_bf16_f32 v12, v12, v13
	v_mfma_f32_16x16x32_bf16 v[68:71], v[170:173], v[226:229], v[68:71]
	v_cvt_pk_bf16_f32 v13, v14, v15
	v_cvt_pk_bf16_f32 v14, v8, v9
	v_cvt_pk_bf16_f32 v15, v10, v11
	ds_bpermute_b32 v8, v100, v12
	ds_bpermute_b32 v9, v100, v13
	ds_bpermute_b32 v10, v100, v14
	v_mfma_f32_16x16x32_bf16 v[64:67], v[178:181], v[226:229], v[64:67]
	ds_bpermute_b32 v11, v100, v15
	s_waitcnt lgkmcnt(4)
	global_store_dwordx4 v152, v[24:27], s[90:91] nt
	v_add_u32_e32 v152, s0, v152
	s_waitcnt lgkmcnt(0)
	global_store_dwordx4 v152, v[8:11], s[90:91] nt
	s_setprio 0
	s_barrier
	s_add_i32 s33, s33, s34
	v_lshl_add_u64 v[152:153], s[14:15], 0, v[132:133]
	s_mov_b32 m0, s33
	ds_read_b128 v[182:185], v156 offset:16384
	ds_read_b128 v[186:189], v156 offset:17408
	ds_read_b128 v[190:193], v156 offset:18432
	ds_read_b128 v[194:197], v156 offset:19456
	ds_read_b128 v[198:201], v156 offset:20480
	ds_read_b128 v[202:205], v156 offset:21504
	ds_read_b128 v[208:211], v156 offset:22528
	ds_read_b128 v[226:229], v156 offset:23552
	global_load_lds_dwordx4 v[152:153], off
	s_add_i32 m0, s33, 0x2000
	s_add_u32 s80, s14, 0x40000
	v_lshl_add_u64 v[212:213], s[14:15], 0, v[136:137]
	s_addc_u32 s81, s15, 0
	s_add_i32 s1, s1, s34
	global_load_lds_dwordx4 v[212:213], off
	v_lshl_add_u64 v[230:231], s[80:81], 0, v[132:133]
	s_mov_b32 m0, s1
	v_lshl_add_u64 v[232:233], s[28:29], 0, v[134:135]
	global_load_lds_dwordx4 v[230:231], off
	v_lshl_add_u64 v[230:231], s[80:81], 0, v[136:137]
	s_add_i32 m0, s1, 0x2000
	s_nop 0
	global_load_lds_dwordx4 v[230:231], off
	v_lshl_add_u64 v[230:231], s[28:29], 0, v[130:131]
	s_mov_b32 m0, s41
	s_nop 0
	global_load_lds_dwordx4 v[230:231], off
	s_mov_b32 m0, s60
	s_nop 0
	global_load_lds_dwordx4 v[232:233], off
	s_waitcnt vmcnt(20)
	s_waitcnt lgkmcnt(0)
	s_barrier
	s_setprio 1
	s_waitcnt lgkmcnt(0)
	v_mfma_f32_16x16x32_bf16 v[60:63], v[144:147], v[182:185], 0
	v_and_b32_e32 v100, 3, v224
	v_lshlrev_b32_e32 v100, 6, v100
	v_and_or_b32 v100, v224, 60, v100
	v_add_u32_e32 v236, s32, v247
	v_fmamk_f32 v234, v240, 0x3a800000, v207
	v_mfma_f32_16x16x32_bf16 v[56:59], v[158:161], v[182:185], 0
	v_rsq_f32_e32 v234, v234
	s_nop 0
	v_mul_f32_e32 v234, s36, v234
	v_mul_f32_e32 v52, v234, v52
	v_mul_f32_e32 v53, v234, v53
	v_mul_f32_e32 v54, v234, v54
	v_mfma_f32_16x16x32_bf16 v[44:47], v[144:147], v[190:193], 0
	v_mul_f32_e32 v55, v234, v55
	v_mul_f32_e32 v48, v234, v48
	v_mul_f32_e32 v49, v234, v49
	v_mul_f32_e32 v50, v234, v50
	v_mul_f32_e32 v51, v234, v51
	v_cvt_pk_bf16_f32 v52, v52, v53
	v_mfma_f32_16x16x32_bf16 v[40:43], v[158:161], v[190:193], 0
	v_cvt_pk_bf16_f32 v53, v54, v55
	v_cvt_pk_bf16_f32 v54, v48, v49
	v_cvt_pk_bf16_f32 v55, v50, v51
	ds_bpermute_b32 v48, v100, v52
	ds_bpermute_b32 v49, v100, v53
	ds_bpermute_b32 v50, v100, v54
	v_mfma_f32_16x16x32_bf16 v[28:31], v[144:147], v[198:201], 0
	ds_bpermute_b32 v51, v100, v55
	v_fmamk_f32 v234, v244, 0x3a800000, v207
	v_rsq_f32_e32 v234, v234
	s_nop 0
	v_mul_f32_e32 v234, s36, v234
	v_mul_f32_e32 v36, v234, v36
	v_mfma_f32_16x16x32_bf16 v[24:27], v[158:161], v[198:201], 0
	v_mul_f32_e32 v37, v234, v37
	v_mul_f32_e32 v38, v234, v38
	v_mul_f32_e32 v39, v234, v39
	v_mul_f32_e32 v32, v234, v32
	v_mul_f32_e32 v33, v234, v33
	v_mul_f32_e32 v34, v234, v34
	v_mfma_f32_16x16x32_bf16 v[12:15], v[144:147], v[208:211], 0
	v_mul_f32_e32 v35, v234, v35
	v_cvt_pk_bf16_f32 v36, v36, v37
	v_cvt_pk_bf16_f32 v37, v38, v39
	v_cvt_pk_bf16_f32 v38, v32, v33
	v_cvt_pk_bf16_f32 v39, v34, v35
	ds_bpermute_b32 v32, v100, v36
	v_mfma_f32_16x16x32_bf16 v[8:11], v[158:161], v[208:211], 0
	ds_bpermute_b32 v33, v100, v37
	ds_bpermute_b32 v34, v100, v38
	ds_bpermute_b32 v35, v100, v39
	s_waitcnt lgkmcnt(4)
	global_store_dwordx4 v236, v[48:51], s[90:91] nt
	v_add_u32_e32 v236, s0, v236
	v_mfma_f32_16x16x32_bf16 v[60:63], v[148:151], v[186:189], v[60:63]
	v_fmamk_f32 v234, v245, 0x3a800000, v207
	v_rsq_f32_e32 v234, v234
	s_nop 0
	v_mul_f32_e32 v234, s36, v234
	v_mul_f32_e32 v20, v234, v20
	v_mul_f32_e32 v21, v234, v21
	v_mfma_f32_16x16x32_bf16 v[56:59], v[162:165], v[186:189], v[56:59]
	v_mul_f32_e32 v22, v234, v22
	v_mul_f32_e32 v23, v234, v23
	v_mul_f32_e32 v16, v234, v16
	v_mul_f32_e32 v17, v234, v17
	v_mul_f32_e32 v18, v234, v18
	v_mul_f32_e32 v19, v234, v19
	v_mfma_f32_16x16x32_bf16 v[44:47], v[148:151], v[194:197], v[44:47]
	v_cvt_pk_bf16_f32 v20, v20, v21
	v_cvt_pk_bf16_f32 v21, v22, v23
	v_cvt_pk_bf16_f32 v22, v16, v17
	v_cvt_pk_bf16_f32 v23, v18, v19
	ds_bpermute_b32 v16, v100, v20
	ds_bpermute_b32 v17, v100, v21
	v_mfma_f32_16x16x32_bf16 v[40:43], v[162:165], v[194:197], v[40:43]
	ds_bpermute_b32 v18, v100, v22
	ds_bpermute_b32 v19, v100, v23
	s_waitcnt lgkmcnt(4)
	global_store_dwordx4 v236, v[32:35], s[90:91] nt
	v_add_u32_e32 v236, s0, v236
	v_fmamk_f32 v234, v246, 0x3a800000, v207
	v_mfma_f32_16x16x32_bf16 v[28:31], v[148:151], v[202:205], v[28:31]
	v_rsq_f32_e32 v234, v234
	s_nop 0
	v_mul_f32_e32 v234, s36, v234
	v_mul_f32_e32 v4, v234, v4
	v_mul_f32_e32 v5, v234, v5
	v_mul_f32_e32 v6, v234, v6
	v_mfma_f32_16x16x32_bf16 v[24:27], v[162:165], v[202:205], v[24:27]
	v_mul_f32_e32 v7, v234, v7
	v_mul_f32_e32 v0, v234, v0
	v_mul_f32_e32 v1, v234, v1
	v_mul_f32_e32 v2, v234, v2
	v_mul_f32_e32 v3, v234, v3
	v_cvt_pk_bf16_f32 v4, v4, v5
	v_mfma_f32_16x16x32_bf16 v[12:15], v[148:151], v[226:229], v[12:15]
	v_cvt_pk_bf16_f32 v5, v6, v7
	v_cvt_pk_bf16_f32 v6, v0, v1
	v_cvt_pk_bf16_f32 v7, v2, v3
	ds_bpermute_b32 v0, v100, v4
	ds_bpermute_b32 v1, v100, v5
	ds_bpermute_b32 v2, v100, v6
	v_mfma_f32_16x16x32_bf16 v[8:11], v[162:165], v[226:229], v[8:11]
	ds_bpermute_b32 v3, v100, v7
	s_waitcnt lgkmcnt(4)
	global_store_dwordx4 v236, v[16:19], s[90:91] nt
	v_add_u32_e32 v236, s0, v236
	s_waitcnt lgkmcnt(0)
	global_store_dwordx4 v236, v[0:3], s[90:91] nt
	s_setprio 0
	s_setprio 1
	v_mfma_f32_16x16x32_bf16 v[52:55], v[166:169], v[182:185], 0
	v_mfma_f32_16x16x32_bf16 v[48:51], v[174:177], v[182:185], 0
	v_mfma_f32_16x16x32_bf16 v[36:39], v[166:169], v[190:193], 0
	v_mfma_f32_16x16x32_bf16 v[32:35], v[174:177], v[190:193], 0
	v_mfma_f32_16x16x32_bf16 v[20:23], v[166:169], v[198:201], 0
	v_mfma_f32_16x16x32_bf16 v[16:19], v[174:177], v[198:201], 0
	v_mfma_f32_16x16x32_bf16 v[4:7], v[166:169], v[208:211], 0
	v_mfma_f32_16x16x32_bf16 v[0:3], v[174:177], v[208:211], 0
	v_mfma_f32_16x16x32_bf16 v[52:55], v[170:173], v[186:189], v[52:55]
	v_mfma_f32_16x16x32_bf16 v[48:51], v[178:181], v[186:189], v[48:51]
	v_mfma_f32_16x16x32_bf16 v[36:39], v[170:173], v[194:197], v[36:39]
	v_mfma_f32_16x16x32_bf16 v[32:35], v[178:181], v[194:197], v[32:35]
	v_mfma_f32_16x16x32_bf16 v[20:23], v[170:173], v[202:205], v[20:23]
	v_mfma_f32_16x16x32_bf16 v[16:19], v[178:181], v[202:205], v[16:19]
	v_mfma_f32_16x16x32_bf16 v[4:7], v[170:173], v[226:229], v[4:7]
	v_mfma_f32_16x16x32_bf16 v[0:3], v[178:181], v[226:229], v[0:3]
	s_setprio 0
	s_barrier
	s_add_i32 s1, 0, 0x18000
	v_add_u32_e32 v100, s1, v154
	s_add_i32 s33, 0, 0x1c000
	ds_read_b128 v[144:147], v100
	ds_read_b128 v[148:151], v100 offset:1024
	ds_read_b128 v[158:161], v100 offset:2048
	ds_read_b128 v[162:165], v100 offset:3072
	v_add_u32_e32 v100, s33, v154
	ds_read_b128 v[166:169], v100
	ds_read_b128 v[170:173], v100 offset:1024
	ds_read_b128 v[174:177], v100 offset:2048
	ds_read_b128 v[178:181], v100 offset:3072
	s_add_u32 s28, s28, 0x40000
	s_addc_u32 s29, s29, 0
	s_mov_b32 m0, s61
	v_lshl_add_u64 v[234:235], s[28:29], 0, v[130:131]
	ds_read_b128 v[182:185], v156 offset:32768
	ds_read_b128 v[186:189], v156 offset:33792
	ds_read_b128 v[190:193], v156 offset:34816
	ds_read_b128 v[194:197], v156 offset:35840
	ds_read_b128 v[198:201], v156 offset:36864
	ds_read_b128 v[202:205], v156 offset:37888
	ds_read_b128 v[208:211], v156 offset:38912
	ds_read_b128 v[226:229], v156 offset:39936
	global_load_lds_dwordx4 v[234:235], off
	v_lshl_add_u64 v[234:235], s[28:29], 0, v[134:135]
	s_mov_b32 m0, s69
	s_nop 0
	global_load_lds_dwordx4 v[234:235], off
	s_lshl_b32 s46, s40, 8
	s_add_i32 s46, s46, s84
	v_or_b32_e32 v100, s46, v139
	v_lshlrev_b32_e32 v100, 2, v100
	global_load_dword v236, v100, s[66:67]
	global_load_dword v237, v100, s[66:67] offset:64
	global_load_dword v238, v100, s[66:67] offset:128
	global_load_dword v239, v100, s[66:67] offset:192
	global_load_dword v240, v100, s[66:67] offset:512
	global_load_dword v244, v100, s[66:67] offset:576
	global_load_dword v245, v100, s[66:67] offset:640
	global_load_dword v246, v100, s[66:67] offset:704
	s_waitcnt vmcnt(32)
	s_waitcnt lgkmcnt(0)
	s_barrier
	s_setprio 1
	s_waitcnt lgkmcnt(0)
	v_mfma_f32_16x16x32_bf16 v[126:129], v[144:147], v[182:185], v[126:129]
	v_mfma_f32_16x16x32_bf16 v[122:125], v[158:161], v[182:185], v[122:125]
	v_mfma_f32_16x16x32_bf16 v[110:113], v[144:147], v[190:193], v[110:113]
	v_mfma_f32_16x16x32_bf16 v[106:109], v[158:161], v[190:193], v[106:109]
	v_mfma_f32_16x16x32_bf16 v[92:95], v[144:147], v[198:201], v[92:95]
	v_mfma_f32_16x16x32_bf16 v[88:91], v[158:161], v[198:201], v[88:91]
	v_mfma_f32_16x16x32_bf16 v[76:79], v[144:147], v[208:211], v[76:79]
	v_mfma_f32_16x16x32_bf16 v[72:75], v[158:161], v[208:211], v[72:75]
	v_mfma_f32_16x16x32_bf16 v[126:129], v[148:151], v[186:189], v[126:129]
	v_mfma_f32_16x16x32_bf16 v[122:125], v[162:165], v[186:189], v[122:125]
	v_mfma_f32_16x16x32_bf16 v[110:113], v[148:151], v[194:197], v[110:113]
	v_mfma_f32_16x16x32_bf16 v[106:109], v[162:165], v[194:197], v[106:109]
	v_mfma_f32_16x16x32_bf16 v[92:95], v[148:151], v[202:205], v[92:95]
	v_mfma_f32_16x16x32_bf16 v[88:91], v[162:165], v[202:205], v[88:91]
	v_mfma_f32_16x16x32_bf16 v[76:79], v[148:151], v[226:229], v[76:79]
	v_mfma_f32_16x16x32_bf16 v[72:75], v[162:165], v[226:229], v[72:75]
	s_setprio 0
	s_setprio 1
	v_mfma_f32_16x16x32_bf16 v[118:121], v[166:169], v[182:185], v[118:121]
	v_mfma_f32_16x16x32_bf16 v[114:117], v[174:177], v[182:185], v[114:117]
	v_mfma_f32_16x16x32_bf16 v[102:105], v[166:169], v[190:193], v[102:105]
	v_mfma_f32_16x16x32_bf16 v[96:99], v[174:177], v[190:193], v[96:99]
	v_mfma_f32_16x16x32_bf16 v[84:87], v[166:169], v[198:201], v[84:87]
	v_mfma_f32_16x16x32_bf16 v[80:83], v[174:177], v[198:201], v[80:83]
	v_mfma_f32_16x16x32_bf16 v[68:71], v[166:169], v[208:211], v[68:71]
	v_mfma_f32_16x16x32_bf16 v[64:67], v[174:177], v[208:211], v[64:67]
	v_mfma_f32_16x16x32_bf16 v[118:121], v[170:173], v[186:189], v[118:121]
	v_mfma_f32_16x16x32_bf16 v[114:117], v[178:181], v[186:189], v[114:117]
	v_mfma_f32_16x16x32_bf16 v[102:105], v[170:173], v[194:197], v[102:105]
	v_mfma_f32_16x16x32_bf16 v[96:99], v[178:181], v[194:197], v[96:99]
	v_mfma_f32_16x16x32_bf16 v[84:87], v[170:173], v[202:205], v[84:87]
	v_mfma_f32_16x16x32_bf16 v[80:83], v[178:181], v[202:205], v[80:83]
	v_mfma_f32_16x16x32_bf16 v[68:71], v[170:173], v[226:229], v[68:71]
	v_mfma_f32_16x16x32_bf16 v[64:67], v[178:181], v[226:229], v[64:67]
	s_setprio 0
	s_barrier
	s_add_i32 s1, s1, s34
	v_lshl_add_u64 v[152:153], v[152:153], 0, s[86:87]
	s_mov_b32 m0, s1
	ds_read_b128 v[182:185], v156 offset:49152
	ds_read_b128 v[186:189], v156 offset:50176
	ds_read_b128 v[190:193], v156 offset:51200
	ds_read_b128 v[194:197], v156 offset:52224
	ds_read_b128 v[198:201], v156 offset:53248
	ds_read_b128 v[202:205], v156 offset:54272
	ds_read_b128 v[208:211], v156 offset:55296
	ds_read_b128 v[226:229], v156 offset:56320
	global_load_lds_dwordx4 v[152:153], off
	s_add_i32 m0, s1, 0x2000
	s_add_u32 s14, s14, 0x40080
	v_lshl_add_u64 v[152:153], v[212:213], 0, s[86:87]
	s_addc_u32 s15, s15, 0
	s_add_i32 s1, s33, s34
	global_load_lds_dwordx4 v[152:153], off
	v_lshl_add_u64 v[152:153], s[14:15], 0, v[132:133]
	s_mov_b32 m0, s1
	s_nop 0
	global_load_lds_dwordx4 v[152:153], off
	v_lshl_add_u64 v[152:153], s[14:15], 0, v[136:137]
	s_add_i32 m0, s1, 0x2000
	s_nop 0
	global_load_lds_dwordx4 v[152:153], off
	v_lshl_add_u64 v[152:153], v[230:231], 0, s[86:87]
	s_mov_b32 m0, s89
	s_nop 0
	global_load_lds_dwordx4 v[152:153], off
	v_lshl_add_u64 v[152:153], v[232:233], 0, s[86:87]
	s_mov_b32 m0, s92
	s_nop 0
	global_load_lds_dwordx4 v[152:153], off
	s_waitcnt vmcnt(20)
	s_waitcnt lgkmcnt(0)
	s_barrier
	s_setprio 1
	s_waitcnt lgkmcnt(0)
	v_mfma_f32_16x16x32_bf16 v[60:63], v[144:147], v[182:185], v[60:63]
	v_mfma_f32_16x16x32_bf16 v[56:59], v[158:161], v[182:185], v[56:59]
	v_mfma_f32_16x16x32_bf16 v[44:47], v[144:147], v[190:193], v[44:47]
	v_mfma_f32_16x16x32_bf16 v[40:43], v[158:161], v[190:193], v[40:43]
	v_mfma_f32_16x16x32_bf16 v[28:31], v[144:147], v[198:201], v[28:31]
	v_mfma_f32_16x16x32_bf16 v[24:27], v[158:161], v[198:201], v[24:27]
	v_mfma_f32_16x16x32_bf16 v[12:15], v[144:147], v[208:211], v[12:15]
	v_mfma_f32_16x16x32_bf16 v[8:11], v[158:161], v[208:211], v[8:11]
	v_mfma_f32_16x16x32_bf16 v[60:63], v[148:151], v[186:189], v[60:63]
	v_mfma_f32_16x16x32_bf16 v[56:59], v[162:165], v[186:189], v[56:59]
	v_mfma_f32_16x16x32_bf16 v[44:47], v[148:151], v[194:197], v[44:47]
	v_mfma_f32_16x16x32_bf16 v[40:43], v[162:165], v[194:197], v[40:43]
	v_mfma_f32_16x16x32_bf16 v[28:31], v[148:151], v[202:205], v[28:31]
	v_mfma_f32_16x16x32_bf16 v[24:27], v[162:165], v[202:205], v[24:27]
	v_mfma_f32_16x16x32_bf16 v[12:15], v[148:151], v[226:229], v[12:15]
	v_mfma_f32_16x16x32_bf16 v[8:11], v[162:165], v[226:229], v[8:11]
	s_setprio 0
	s_setprio 1
	v_mfma_f32_16x16x32_bf16 v[52:55], v[166:169], v[182:185], v[52:55]
	v_mfma_f32_16x16x32_bf16 v[48:51], v[174:177], v[182:185], v[48:51]
	v_mfma_f32_16x16x32_bf16 v[36:39], v[166:169], v[190:193], v[36:39]
	v_mfma_f32_16x16x32_bf16 v[32:35], v[174:177], v[190:193], v[32:35]
	v_mfma_f32_16x16x32_bf16 v[20:23], v[166:169], v[198:201], v[20:23]
	v_mfma_f32_16x16x32_bf16 v[16:19], v[174:177], v[198:201], v[16:19]
	v_mfma_f32_16x16x32_bf16 v[4:7], v[166:169], v[208:211], v[4:7]
	v_mfma_f32_16x16x32_bf16 v[0:3], v[174:177], v[208:211], v[0:3]
	v_mfma_f32_16x16x32_bf16 v[52:55], v[170:173], v[186:189], v[52:55]
	v_mfma_f32_16x16x32_bf16 v[48:51], v[178:181], v[186:189], v[48:51]
	v_mfma_f32_16x16x32_bf16 v[36:39], v[170:173], v[194:197], v[36:39]
	v_mfma_f32_16x16x32_bf16 v[32:35], v[178:181], v[194:197], v[32:35]
	v_mfma_f32_16x16x32_bf16 v[20:23], v[170:173], v[202:205], v[20:23]
	v_mfma_f32_16x16x32_bf16 v[16:19], v[178:181], v[202:205], v[16:19]
	v_mfma_f32_16x16x32_bf16 v[4:7], v[170:173], v[226:229], v[4:7]
	v_mfma_f32_16x16x32_bf16 v[0:3], v[178:181], v[226:229], v[0:3]
	s_setprio 0
	s_barrier
	s_add_i32 s73, s73, 2
	s_add_u32 s12, s12, 0x100
	s_addc_u32 s13, s13, 0
	s_add_u32 s54, s54, 0x100
	s_addc_u32 s55, s55, 0
